# XCD-local seams: L1 invalidate issued with the arrival atomic, leader publishes the release straight away
# baseline (speedup 1.0000x reference)
.LBB0_427:
	s_or_b64 exec, exec, s[12:13]
	buffer_inv sc1
	v_cvt_f32_u32_e32 v4, v2
	s_waitcnt vmcnt(0)
	v_readfirstlane_b32 s0, v3
	v_sub_u32_e32 v3, 0, v2
	v_rcp_iflag_f32_e32 v4, v4
	v_add_u32_e32 v5, s0, v1
	v_mul_f32_e32 v4, 0x4f7ffffe, v4
	v_cvt_u32_f32_e32 v4, v4
	v_mul_lo_u32 v1, v3, v4
	v_mul_hi_u32 v1, v4, v1
	v_add_u32_e32 v1, v4, v1
	v_mul_hi_u32 v1, v5, v1
	v_mul_lo_u32 v3, v1, v2
	v_sub_u32_e32 v3, v5, v3
	v_add_u32_e32 v4, 1, v1
	v_cmp_ge_u32_e32 vcc, v3, v2
	s_nop 1
	v_cndmask_b32_e32 v1, v1, v4, vcc
	v_sub_u32_e32 v4, v3, v2
	v_cndmask_b32_e32 v3, v3, v4, vcc
	v_add_u32_e32 v4, 1, v1
	v_cmp_ge_u32_e32 vcc, v3, v2
	v_add_u32_e32 v3, 1, v5
	s_nop 0
	v_cndmask_b32_e32 v1, v1, v4, vcc
	v_mul_lo_u32 v4, v2, v1
	v_add_u32_e32 v2, v4, v2
	v_cmp_ne_u32_e32 vcc, v3, v2
	s_and_saveexec_b64 s[0:1], vcc
	s_xor_b64 s[10:11], exec, s[0:1]
	s_cbranch_execz .LBB0_441
	s_waitcnt lgkmcnt(0)
	v_mov_b32_e32 v0, 0x2000
	global_load_dword v0, v0, s[8:9] offset:1024 sc1
	s_add_u32 s16, s8, 0x2400
	s_addc_u32 s17, s9, 0
	s_waitcnt vmcnt(0)
	v_cmp_eq_u32_e32 vcc, v0, v1
	s_and_saveexec_b64 s[12:13], vcc
	s_cbranch_execz .LBB0_440
	s_add_u32 s14, s54, 0x4200
	s_addc_u32 s15, s55, 0
	s_mov_b32 s0, 1
	s_mov_b64 s[18:19], 0
	v_mov_b32_e32 v0, 0
	s_branch .LBB0_431

.LBB0_441:
	s_andn2_saveexec_b64 s[0:1], s[10:11]
	s_cbranch_execz .LBB0_461
	s_mov_b64 s[10:11], exec
	v_readlane_b32 s0, v248, 20
	s_cmp_eq_u32 s0, 1
	s_cbranch_scc0 .Lglob_4
	s_branch .Lloc_4
